# phase 1 p->bf16 copy batched (8 loads in flight); phase 12 residual RMW through LDS transpose (row-contiguous)
# speedup vs baseline: 1.0100x; 1.0100x over previous
.LBB0_281:
	s_mov_b32 s5, 0x100000
	v_cmp_gt_i32_e32 vcc, s5, v4
	s_and_saveexec_b64 s[6:7], vcc
	s_cbranch_execz .LBB0_284
	v_readlane_b32 s8, v254, 30
	v_readlane_b32 s9, v254, 31
	s_lshl_b64 s[10:11], s[8:9], 24
	v_lshl_add_u64 v[0:1], v[4:5], 3, s[0:1]
	s_mov_b64 s[8:9], 0xe400004
	s_ashr_i32 s5, s4, 31
	v_lshl_add_u64 v[0:1], v[0:1], 0, s[8:9]
	s_lshl_b64 s[8:9], s[4:5], 3
	v_readlane_b32 s12, v254, 4
	s_add_u32 s10, s12, s10
	v_readlane_b32 s12, v254, 5
	s_addc_u32 s11, s12, s11
	v_lshl_add_u64 v[2:3], v[4:5], 4, s[10:11]
	s_lshl_b64 s[10:11], s[4:5], 4
	s_mov_b64 s[12:13], 0
	s_cmpk_lg_i32 s90, 0x200
	s_cbranch_scc1 .LBB0_283
	global_load_dwordx4 v[6:9], v[2:3], off offset:-8
	v_lshl_add_u64 v[2:3], v[2:3], 0, s[10:11]
	global_load_dwordx4 v[10:13], v[2:3], off offset:-8
	v_lshl_add_u64 v[2:3], v[2:3], 0, s[10:11]
	global_load_dwordx4 v[14:17], v[2:3], off offset:-8
	v_lshl_add_u64 v[2:3], v[2:3], 0, s[10:11]
	global_load_dwordx4 v[18:21], v[2:3], off offset:-8
	v_lshl_add_u64 v[2:3], v[2:3], 0, s[10:11]
	global_load_dwordx4 v[22:25], v[2:3], off offset:-8
	v_lshl_add_u64 v[2:3], v[2:3], 0, s[10:11]
	global_load_dwordx4 v[26:29], v[2:3], off offset:-8
	v_lshl_add_u64 v[2:3], v[2:3], 0, s[10:11]
	global_load_dwordx4 v[30:33], v[2:3], off offset:-8
	v_lshl_add_u64 v[2:3], v[2:3], 0, s[10:11]
	global_load_dwordx4 v[34:37], v[2:3], off offset:-8
	s_waitcnt vmcnt(7)
	v_cvt_pk_bf16_f32 v6, v6, v7
	v_cvt_pk_bf16_f32 v7, v8, v9
	global_store_dwordx2 v[0:1], v[6:7], off offset:-4
	v_lshl_add_u64 v[0:1], v[0:1], 0, s[8:9]
	s_waitcnt vmcnt(7)
	v_cvt_pk_bf16_f32 v10, v10, v11
	v_cvt_pk_bf16_f32 v11, v12, v13
	global_store_dwordx2 v[0:1], v[10:11], off offset:-4
	v_lshl_add_u64 v[0:1], v[0:1], 0, s[8:9]
	s_waitcnt vmcnt(7)
	v_cvt_pk_bf16_f32 v14, v14, v15
	v_cvt_pk_bf16_f32 v15, v16, v17
	global_store_dwordx2 v[0:1], v[14:15], off offset:-4
	v_lshl_add_u64 v[0:1], v[0:1], 0, s[8:9]
	s_waitcnt vmcnt(7)
	v_cvt_pk_bf16_f32 v18, v18, v19
	v_cvt_pk_bf16_f32 v19, v20, v21
	global_store_dwordx2 v[0:1], v[18:19], off offset:-4
	v_lshl_add_u64 v[0:1], v[0:1], 0, s[8:9]
	s_waitcnt vmcnt(7)
	v_cvt_pk_bf16_f32 v22, v22, v23
	v_cvt_pk_bf16_f32 v23, v24, v25
	global_store_dwordx2 v[0:1], v[22:23], off offset:-4
	v_lshl_add_u64 v[0:1], v[0:1], 0, s[8:9]
	s_waitcnt vmcnt(7)
	v_cvt_pk_bf16_f32 v26, v26, v27
	v_cvt_pk_bf16_f32 v27, v28, v29
	global_store_dwordx2 v[0:1], v[26:27], off offset:-4
	v_lshl_add_u64 v[0:1], v[0:1], 0, s[8:9]
	s_waitcnt vmcnt(7)
	v_cvt_pk_bf16_f32 v30, v30, v31
	v_cvt_pk_bf16_f32 v31, v32, v33
	global_store_dwordx2 v[0:1], v[30:31], off offset:-4
	v_lshl_add_u64 v[0:1], v[0:1], 0, s[8:9]
	s_waitcnt vmcnt(7)
	v_cvt_pk_bf16_f32 v34, v34, v35
	v_cvt_pk_bf16_f32 v35, v36, v37
	global_store_dwordx2 v[0:1], v[34:35], off offset:-4
	s_branch .LBB0_284

.LBB0_2453:
	s_lshl_b32 s0, s4, 7
	s_ashr_i32 s1, s0, 31
	s_lshl_b32 s2, s2, 6
	s_lshl_b64 s[4:5], s[0:1], 9
	v_mov_b32_e32 v0, v161
	s_add_u32 s4, s10, s4
	v_mov_b32_e32 v1, v186
	s_addc_u32 s5, s11, s5
	s_ashr_i32 s3, s2, 31
	s_lshl_b64 s[6:7], s[2:3], 9
	v_lshlrev_b32_e32 v2, 4, v1
	s_waitcnt vmcnt(17)
	v_ashrrev_i32_e32 v27, 3, v1
	v_and_b32_e32 v26, 0x70, v2
	s_add_u32 s6, s12, s6
	v_lshl_or_b32 v119, v27, 9, v26
	s_addc_u32 s7, s13, s7
	v_add_u32_e32 v120, 0x4000, v119
	v_add_u32_e32 v121, 0x8000, v119
	v_add_u32_e32 v122, 0xc000, v119
	s_barrier
	s_lshl_b32 s72, s0, 5
	s_add_u32 s72, s72, 0xed00000
	s_add_u32 s72, s88, s72
	s_addc_u32 s73, s89, 0
	global_load_dwordx4 v[210:213], v248, s[72:73]
	global_load_dwordx4 v[214:217], v248, s[72:73] offset:16
	global_load_dwordx4 v[226:229], v248, s[72:73] offset:1024
	global_load_dwordx4 v[230:233], v248, s[72:73] offset:1040
	global_load_dwordx4 v[2:5], v119, s[4:5]
	global_load_dwordx4 v[6:9], v120, s[4:5]
	global_load_dwordx4 v[10:13], v121, s[4:5]
	global_load_dwordx4 v[14:17], v122, s[4:5]
	global_load_dwordx4 v[18:21], v119, s[6:7]
	global_load_dwordx4 v[22:25], v120, s[6:7]
	v_mad_u64_u32 v[84:85], s[18:19], v27, s43, v[26:27]
	s_waitcnt vmcnt(5)
	ds_write_b128 v84, v[2:5]
	s_waitcnt vmcnt(4)
	ds_write_b128 v84, v[6:9] offset:4608
	s_waitcnt vmcnt(3)
	ds_write_b128 v84, v[10:13] offset:9216
	s_waitcnt vmcnt(2)
	ds_write_b128 v84, v[14:17] offset:13824
	s_waitcnt vmcnt(1)
	ds_write_b128 v84, v[18:21] offset:36864
	s_waitcnt vmcnt(0)
	ds_write_b128 v84, v[22:25] offset:41472
	global_load_dwordx4 v[40:43], v119, s[4:5] offset:128
	global_load_dwordx4 v[44:47], v120, s[4:5] offset:128
	global_load_dwordx4 v[48:51], v121, s[4:5] offset:128
	global_load_dwordx4 v[52:55], v122, s[4:5] offset:128
	global_load_dwordx4 v[32:35], v119, s[6:7] offset:128
	global_load_dwordx4 v[36:39], v120, s[6:7] offset:128
	v_lshrrev_b32_e32 v3, 1, v1
	v_and_b32_e32 v1, 31, v1
	v_and_or_b32 v4, v3, 32, v1
	v_and_b32_e32 v2, 16, v3
	v_and_or_b32 v1, v3, s44, v1
	v_mad_u64_u32 v[82:83], s[18:19], v1, s43, v[2:3]
	s_waitcnt lgkmcnt(0)
	s_barrier
	ds_read_b128 v[56:59], v82 offset:4608
	ds_read_b128 v[60:63], v82
	v_mad_u32_u24 v85, v4, s43, v2
	ds_read_b128 v[124:127], v82 offset:32
	ds_read_b128 v[64:67], v85 offset:36864
	ds_read_b128 v[128:131], v82 offset:4640
	v_mov_b32_e32 v1, v0
	v_mov_b32_e32 v2, v0
	v_mov_b32_e32 v3, v0
	v_mov_b32_e32 v4, v0
	v_mov_b32_e32 v5, v0
	v_mov_b32_e32 v6, v0
	v_mov_b32_e32 v7, v0
	v_mov_b32_e32 v8, v0
	v_mov_b32_e32 v9, v0
	v_mov_b32_e32 v10, v0
	v_mov_b32_e32 v11, v0
	v_mov_b32_e32 v12, v0
	v_mov_b32_e32 v13, v0
	v_mov_b32_e32 v14, v0
	v_mov_b32_e32 v15, v0
	ds_read_b128 v[132:135], v85 offset:36896
	s_waitcnt lgkmcnt(2)
	v_mfma_f32_32x32x16_bf16 v[16:31], v[64:67], v[60:63], v[0:15]
	v_mfma_f32_32x32x16_bf16 v[0:15], v[64:67], v[56:59], v[0:15]
	s_waitcnt lgkmcnt(0)
	v_mfma_f32_32x32x16_bf16 v[16:31], v[132:135], v[124:127], v[16:31]
	v_mfma_f32_32x32x16_bf16 v[0:15], v[132:135], v[128:131], v[0:15]
	ds_read_b128 v[136:139], v82 offset:64
	ds_read_b128 v[140:143], v82 offset:4672
	ds_read_b128 v[144:147], v85 offset:36928
	s_waitcnt lgkmcnt(0)
	v_mfma_f32_32x32x16_bf16 v[16:31], v[144:147], v[136:139], v[16:31]
	v_mfma_f32_32x32x16_bf16 v[0:15], v[144:147], v[140:143], v[0:15]
	global_load_dwordx4 v[64:67], v119, s[4:5] offset:256
	global_load_dwordx4 v[68:71], v120, s[4:5] offset:256
	global_load_dwordx4 v[72:75], v121, s[4:5] offset:256
	global_load_dwordx4 v[76:79], v122, s[4:5] offset:256
	global_load_dwordx4 v[56:59], v119, s[6:7] offset:256
	global_load_dwordx4 v[60:63], v120, s[6:7] offset:256
	s_waitcnt vmcnt(11)
	ds_write_b128 v84, v[40:43] offset:18432
	s_waitcnt vmcnt(10)
	ds_write_b128 v84, v[44:47] offset:23040
	s_waitcnt vmcnt(9)
	ds_write_b128 v84, v[48:51] offset:27648
	s_waitcnt vmcnt(8)
	ds_write_b128 v84, v[52:55] offset:32256
	ds_read_b128 v[40:43], v82 offset:96
	ds_read_b128 v[44:47], v82 offset:4704
	ds_read_b128 v[48:51], v85 offset:36960
	s_waitcnt vmcnt(7)
	ds_write_b128 v84, v[32:35] offset:46080
	s_waitcnt vmcnt(6)
	ds_write_b128 v84, v[36:39] offset:50688
	s_waitcnt lgkmcnt(2)
	v_mfma_f32_32x32x16_bf16 v[16:31], v[48:51], v[40:43], v[16:31]
	s_waitcnt lgkmcnt(0)
	s_barrier
	v_mfma_f32_32x32x16_bf16 v[0:15], v[48:51], v[44:47], v[0:15]
	ds_read_b128 v[32:35], v82 offset:23040
	ds_read_b128 v[36:39], v82 offset:18432
	ds_read_b128 v[48:51], v85 offset:46080
	ds_read_b128 v[40:43], v82 offset:18464
	ds_read_b128 v[44:47], v82 offset:23072
	ds_read_b128 v[52:55], v85 offset:46112
	s_waitcnt lgkmcnt(3)
	v_mfma_f32_32x32x16_bf16 v[16:31], v[48:51], v[36:39], v[16:31]
	v_mfma_f32_32x32x16_bf16 v[0:15], v[48:51], v[32:35], v[0:15]
	global_load_dwordx4 v[32:35], v119, s[4:5] offset:384
	global_load_dwordx4 v[36:39], v120, s[4:5] offset:384
	global_load_dwordx4 v[48:51], v121, s[4:5] offset:384
	global_load_dwordx4 v[126:129], v119, s[6:7] offset:384
	global_load_dwordx4 v[130:133], v120, s[6:7] offset:384
	s_nop 0
	global_load_dwordx4 v[122:125], v122, s[4:5] offset:384
	ds_read_b128 v[134:137], v82 offset:18496
	ds_read_b128 v[138:141], v82 offset:23104
	ds_read_b128 v[142:145], v85 offset:46144
	s_lshl_b64 s[4:5], s[0:1], 11
	s_add_u32 s4, s8, s4
	s_addc_u32 s5, s9, s5
	s_lshl_b64 s[6:7], s[2:3], 11
	s_add_u32 s6, s14, s6
	s_addc_u32 s7, s15, s7
	s_waitcnt vmcnt(11)
	ds_write_b128 v84, v[64:67]
	s_waitcnt vmcnt(10)
	ds_write_b128 v84, v[68:71] offset:4608
	s_waitcnt vmcnt(9)
	ds_write_b128 v84, v[72:75] offset:9216
	s_waitcnt vmcnt(8)
	ds_write_b128 v84, v[76:79] offset:13824
	s_waitcnt lgkmcnt(7)
	v_mfma_f32_32x32x16_bf16 v[16:31], v[52:55], v[40:43], v[16:31]
	v_mfma_f32_32x32x16_bf16 v[0:15], v[52:55], v[44:47], v[0:15]
	ds_read_b128 v[40:43], v82 offset:18528
	ds_read_b128 v[44:47], v82 offset:23136
	ds_read_b128 v[52:55], v85 offset:46176
	s_waitcnt vmcnt(7)
	ds_write_b128 v84, v[56:59] offset:36864
	s_waitcnt vmcnt(6)
	ds_write_b128 v84, v[60:63] offset:41472
	s_waitcnt lgkmcnt(0)
	s_barrier
	v_mfma_f32_32x32x16_bf16 v[16:31], v[142:145], v[134:137], v[16:31]
	v_mfma_f32_32x32x16_bf16 v[0:15], v[142:145], v[138:141], v[0:15]
	v_mfma_f32_32x32x16_bf16 v[16:31], v[52:55], v[40:43], v[16:31]
	v_mfma_f32_32x32x16_bf16 v[0:15], v[52:55], v[44:47], v[0:15]
	ds_read_b128 v[40:43], v82 offset:4608
	ds_read_b128 v[56:59], v82
	ds_read_b128 v[44:47], v85 offset:36864
	ds_read_b128 v[52:55], v85 offset:36896
	ds_read_b128 v[60:63], v82 offset:32
	ds_read_b128 v[64:67], v85 offset:36928
	s_waitcnt lgkmcnt(3)
	v_mfma_f32_32x32x16_bf16 v[16:31], v[44:47], v[56:59], v[16:31]
	v_mfma_f32_32x32x16_bf16 v[0:15], v[44:47], v[40:43], v[0:15]
	ds_read_b128 v[40:43], v82 offset:4640
	ds_read_b128 v[44:47], v82 offset:64
	ds_read_b128 v[56:59], v82 offset:4672
	s_waitcnt vmcnt(5)
	ds_write_b128 v84, v[32:35] offset:18432
	s_waitcnt vmcnt(4)
	ds_write_b128 v84, v[36:39] offset:23040
	s_waitcnt vmcnt(3)
	ds_write_b128 v84, v[48:51] offset:27648
	s_waitcnt vmcnt(0)
	ds_write_b128 v84, v[122:125] offset:32256
	s_waitcnt lgkmcnt(8)
	v_mfma_f32_32x32x16_bf16 v[16:31], v[52:55], v[60:63], v[16:31]
	s_waitcnt lgkmcnt(6)
	v_mfma_f32_32x32x16_bf16 v[0:15], v[52:55], v[40:43], v[0:15]
	ds_read_b128 v[32:35], v82 offset:96
	ds_read_b128 v[36:39], v82 offset:4704
	ds_read_b128 v[40:43], v85 offset:36960
	ds_write_b128 v84, v[126:129] offset:46080
	ds_write_b128 v84, v[130:133] offset:50688
	s_waitcnt lgkmcnt(0)
	s_barrier
	v_mfma_f32_32x32x16_bf16 v[16:31], v[64:67], v[44:47], v[16:31]
	v_mfma_f32_32x32x16_bf16 v[0:15], v[64:67], v[56:59], v[0:15]
	v_mfma_f32_32x32x16_bf16 v[16:31], v[40:43], v[32:35], v[16:31]
	v_mfma_f32_32x32x16_bf16 v[0:15], v[40:43], v[36:39], v[0:15]
	ds_read_b128 v[32:35], v82 offset:23040
	ds_read_b128 v[36:39], v82 offset:18432
	ds_read_b128 v[48:51], v85 offset:46080
	ds_read_b128 v[44:47], v82 offset:23072
	ds_read_b128 v[40:43], v82 offset:18464
	ds_read_b128 v[52:55], v85 offset:46112
	s_waitcnt lgkmcnt(3)
	v_mfma_f32_32x32x16_bf16 v[0:15], v[48:51], v[32:35], v[0:15]
	v_mfma_f32_32x32x16_bf16 v[16:31], v[48:51], v[36:39], v[16:31]
	ds_read_b128 v[36:39], v82 offset:23104
	ds_read_b128 v[32:35], v82 offset:18496
	ds_read_b128 v[48:51], v85 offset:46144
	s_waitcnt lgkmcnt(3)
	v_mfma_f32_32x32x16_bf16 v[0:15], v[52:55], v[44:47], v[0:15]
	v_mfma_f32_32x32x16_bf16 v[16:31], v[52:55], v[40:43], v[16:31]
	ds_read_b128 v[60:63], v82 offset:23136
	ds_read_b128 v[56:59], v82 offset:18528
	ds_read_b128 v[64:67], v85 offset:46176
	s_waitcnt lgkmcnt(0)
	s_barrier
	v_mfma_f32_32x32x16_bf16 v[0:15], v[48:51], v[36:39], v[0:15]
	v_mfma_f32_32x32x16_bf16 v[16:31], v[48:51], v[32:35], v[16:31]
	v_mfma_f32_32x32x16_bf16 v[0:15], v[64:67], v[60:63], v[0:15]
	v_mfma_f32_32x32x16_bf16 v[16:31], v[64:67], v[56:59], v[16:31]
	s_nop 10
	v_cvt_pk_bf16_f32 v126, v0, v1
	v_mov_b32_e32 v0, v161
	v_mov_b32_e32 v1, v186
	v_cvt_pk_bf16_f32 v125, v2, v3
	v_cvt_pk_bf16_f32 v124, v4, v5
	v_lshlrev_b32_e32 v2, 4, v1
	v_cvt_pk_bf16_f32 v129, v26, v27
	v_ashrrev_i32_e32 v27, 3, v1
	v_and_b32_e32 v26, 0x70, v2
	v_lshl_or_b32 v135, v27, 11, v26
	v_add_u32_e32 v136, 0x10000, v135
	v_add_u32_e32 v137, 0x20000, v135
	v_add_u32_e32 v138, 0x30000, v135
	v_cvt_pk_bf16_f32 v134, v16, v17
	v_cvt_pk_bf16_f32 v133, v18, v19
	v_cvt_pk_bf16_f32 v132, v20, v21
	v_cvt_pk_bf16_f32 v131, v22, v23
	v_cvt_pk_bf16_f32 v130, v24, v25
	v_cvt_pk_bf16_f32 v123, v6, v7
	v_cvt_pk_bf16_f32 v122, v8, v9
	v_cvt_pk_bf16_f32 v121, v10, v11
	v_cvt_pk_bf16_f32 v120, v12, v13
	v_cvt_pk_bf16_f32 v119, v14, v15
	s_barrier
	global_load_dwordx4 v[2:5], v135, s[4:5]
	global_load_dwordx4 v[6:9], v136, s[4:5]
	global_load_dwordx4 v[10:13], v137, s[4:5]
	global_load_dwordx4 v[14:17], v138, s[4:5]
	global_load_dwordx4 v[18:21], v135, s[6:7]
	global_load_dwordx4 v[22:25], v136, s[6:7]
	v_mad_u64_u32 v[82:83], s[18:19], v27, s43, v[26:27]
	v_cvt_pk_bf16_f32 v128, v28, v29
	v_cvt_pk_bf16_f32 v127, v30, v31
	s_waitcnt vmcnt(5)
	ds_write_b128 v82, v[2:5]
	s_waitcnt vmcnt(4)
	ds_write_b128 v82, v[6:9] offset:4608
	s_waitcnt vmcnt(3)
	ds_write_b128 v82, v[10:13] offset:9216
	s_waitcnt vmcnt(2)
	ds_write_b128 v82, v[14:17] offset:13824
	s_waitcnt vmcnt(1)
	ds_write_b128 v82, v[18:21] offset:36864
	s_waitcnt vmcnt(0)
	ds_write_b128 v82, v[22:25] offset:41472
	global_load_dwordx4 v[40:43], v135, s[4:5] offset:128
	global_load_dwordx4 v[44:47], v136, s[4:5] offset:128
	global_load_dwordx4 v[48:51], v137, s[4:5] offset:128
	global_load_dwordx4 v[52:55], v138, s[4:5] offset:128
	global_load_dwordx4 v[32:35], v135, s[6:7] offset:128
	global_load_dwordx4 v[36:39], v136, s[6:7] offset:128
	v_lshrrev_b32_e32 v3, 1, v1
	v_and_b32_e32 v1, 31, v1
	v_and_or_b32 v4, v3, 32, v1
	v_and_b32_e32 v2, 16, v3
	v_and_or_b32 v1, v3, s44, v1
	v_mad_u64_u32 v[84:85], s[18:19], v1, s43, v[2:3]
	s_waitcnt lgkmcnt(0)
	s_barrier
	ds_read_b128 v[56:59], v84 offset:4608
	ds_read_b128 v[60:63], v84
	v_mad_u32_u24 v83, v4, s43, v2
	ds_read_b128 v[140:143], v84 offset:32
	ds_read_b128 v[64:67], v83 offset:36864
	ds_read_b128 v[144:147], v84 offset:4640
	v_mov_b32_e32 v1, v0
	v_mov_b32_e32 v2, v0
	v_mov_b32_e32 v3, v0
	v_mov_b32_e32 v4, v0
	v_mov_b32_e32 v5, v0
	v_mov_b32_e32 v6, v0
	v_mov_b32_e32 v7, v0
	v_mov_b32_e32 v8, v0
	v_mov_b32_e32 v9, v0
	v_mov_b32_e32 v10, v0
	v_mov_b32_e32 v11, v0
	v_mov_b32_e32 v12, v0
	v_mov_b32_e32 v13, v0
	v_mov_b32_e32 v14, v0
	v_mov_b32_e32 v15, v0
	ds_read_b128 v[148:151], v83 offset:36896
	s_waitcnt lgkmcnt(2)
	v_mfma_f32_32x32x16_bf16 v[16:31], v[64:67], v[60:63], v[0:15]
	v_mfma_f32_32x32x16_bf16 v[0:15], v[64:67], v[56:59], v[0:15]
	s_waitcnt lgkmcnt(0)
	v_mfma_f32_32x32x16_bf16 v[16:31], v[148:151], v[140:143], v[16:31]
	v_mfma_f32_32x32x16_bf16 v[0:15], v[148:151], v[144:147], v[0:15]
	ds_read_b128 v[152:155], v84 offset:64
	ds_read_b128 v[156:159], v84 offset:4672
	ds_read_b128 v[164:167], v83 offset:36928
	s_waitcnt lgkmcnt(0)
	v_mfma_f32_32x32x16_bf16 v[16:31], v[164:167], v[152:155], v[16:31]
	v_mfma_f32_32x32x16_bf16 v[0:15], v[164:167], v[156:159], v[0:15]
	global_load_dwordx4 v[64:67], v135, s[4:5] offset:256
	global_load_dwordx4 v[68:71], v136, s[4:5] offset:256
	global_load_dwordx4 v[72:75], v137, s[4:5] offset:256
	global_load_dwordx4 v[76:79], v138, s[4:5] offset:256
	global_load_dwordx4 v[56:59], v135, s[6:7] offset:256
	global_load_dwordx4 v[60:63], v136, s[6:7] offset:256
	s_waitcnt vmcnt(11)
	ds_write_b128 v82, v[40:43] offset:18432
	s_waitcnt vmcnt(10)
	ds_write_b128 v82, v[44:47] offset:23040
	s_waitcnt vmcnt(9)
	ds_write_b128 v82, v[48:51] offset:27648
	s_waitcnt vmcnt(8)
	ds_write_b128 v82, v[52:55] offset:32256
	ds_read_b128 v[40:43], v84 offset:96
	ds_read_b128 v[44:47], v84 offset:4704
	ds_read_b128 v[48:51], v83 offset:36960
	s_waitcnt vmcnt(7)
	ds_write_b128 v82, v[32:35] offset:46080
	s_waitcnt vmcnt(6)
	ds_write_b128 v82, v[36:39] offset:50688
	s_waitcnt lgkmcnt(2)
	v_mfma_f32_32x32x16_bf16 v[16:31], v[48:51], v[40:43], v[16:31]
	s_waitcnt lgkmcnt(0)
	s_barrier
	v_mfma_f32_32x32x16_bf16 v[0:15], v[48:51], v[44:47], v[0:15]
	ds_read_b128 v[32:35], v84 offset:23040
	ds_read_b128 v[36:39], v84 offset:18432
	ds_read_b128 v[48:51], v83 offset:46080
	ds_read_b128 v[40:43], v84 offset:18464
	ds_read_b128 v[44:47], v84 offset:23072
	ds_read_b128 v[52:55], v83 offset:46112
	s_waitcnt lgkmcnt(3)
	v_mfma_f32_32x32x16_bf16 v[16:31], v[48:51], v[36:39], v[16:31]
	v_mfma_f32_32x32x16_bf16 v[0:15], v[48:51], v[32:35], v[0:15]
	global_load_dwordx4 v[32:35], v135, s[4:5] offset:384
	global_load_dwordx4 v[36:39], v136, s[4:5] offset:384
	global_load_dwordx4 v[48:51], v137, s[4:5] offset:384
	global_load_dwordx4 v[140:143], v138, s[4:5] offset:384
	global_load_dwordx4 v[144:147], v135, s[6:7] offset:384
	global_load_dwordx4 v[148:151], v136, s[6:7] offset:384
	ds_read_b128 v[152:155], v84 offset:18496
	ds_read_b128 v[156:159], v84 offset:23104
	ds_read_b128 v[164:167], v83 offset:46144
	s_waitcnt vmcnt(11)
	ds_write_b128 v82, v[64:67]
	s_waitcnt vmcnt(10)
	ds_write_b128 v82, v[68:71] offset:4608
	s_waitcnt vmcnt(9)
	ds_write_b128 v82, v[72:75] offset:9216
	s_waitcnt vmcnt(8)
	ds_write_b128 v82, v[76:79] offset:13824
	s_waitcnt lgkmcnt(7)
	v_mfma_f32_32x32x16_bf16 v[16:31], v[52:55], v[40:43], v[16:31]
	v_mfma_f32_32x32x16_bf16 v[0:15], v[52:55], v[44:47], v[0:15]
	ds_read_b128 v[40:43], v84 offset:18528
	ds_read_b128 v[44:47], v84 offset:23136
	ds_read_b128 v[52:55], v83 offset:46176
	s_waitcnt vmcnt(7)
	ds_write_b128 v82, v[56:59] offset:36864
	s_waitcnt vmcnt(6)
	ds_write_b128 v82, v[60:63] offset:41472
	s_waitcnt lgkmcnt(0)
	s_barrier
	v_mfma_f32_32x32x16_bf16 v[16:31], v[164:167], v[152:155], v[16:31]
	v_mfma_f32_32x32x16_bf16 v[0:15], v[164:167], v[156:159], v[0:15]
	v_mfma_f32_32x32x16_bf16 v[16:31], v[52:55], v[40:43], v[16:31]
	v_mfma_f32_32x32x16_bf16 v[0:15], v[52:55], v[44:47], v[0:15]
	ds_read_b128 v[40:43], v84 offset:4608
	ds_read_b128 v[44:47], v84
	ds_read_b128 v[60:63], v83 offset:36864
	ds_read_b128 v[52:55], v84 offset:32
	ds_read_b128 v[56:59], v84 offset:4640
	ds_read_b128 v[64:67], v83 offset:36896
	s_waitcnt lgkmcnt(3)
	v_mfma_f32_32x32x16_bf16 v[16:31], v[60:63], v[44:47], v[16:31]
	v_mfma_f32_32x32x16_bf16 v[0:15], v[60:63], v[40:43], v[0:15]
	global_load_dwordx4 v[40:43], v135, s[4:5] offset:512
	global_load_dwordx4 v[44:47], v136, s[4:5] offset:512
	global_load_dwordx4 v[60:63], v137, s[4:5] offset:512
	global_load_dwordx4 v[68:71], v138, s[4:5] offset:512
	global_load_dwordx4 v[72:75], v135, s[6:7] offset:512
	global_load_dwordx4 v[76:79], v136, s[6:7] offset:512
	ds_read_b128 v[152:155], v84 offset:64
	ds_read_b128 v[156:159], v84 offset:4672
	ds_read_b128 v[164:167], v83 offset:36928
	s_waitcnt vmcnt(11)
	ds_write_b128 v82, v[32:35] offset:18432
	s_waitcnt vmcnt(10)
	ds_write_b128 v82, v[36:39] offset:23040
	s_waitcnt vmcnt(9)
	ds_write_b128 v82, v[48:51] offset:27648
	s_waitcnt vmcnt(8)
	ds_write_b128 v82, v[140:143] offset:32256
	s_waitcnt lgkmcnt(7)
	v_mfma_f32_32x32x16_bf16 v[16:31], v[64:67], v[52:55], v[16:31]
	v_mfma_f32_32x32x16_bf16 v[0:15], v[64:67], v[56:59], v[0:15]
	ds_read_b128 v[32:35], v84 offset:96
	ds_read_b128 v[36:39], v84 offset:4704
	ds_read_b128 v[48:51], v83 offset:36960
	s_waitcnt vmcnt(7)
	ds_write_b128 v82, v[144:147] offset:46080
	s_waitcnt vmcnt(6)
	ds_write_b128 v82, v[148:151] offset:50688
	s_waitcnt lgkmcnt(0)
	s_barrier
	v_mfma_f32_32x32x16_bf16 v[16:31], v[164:167], v[152:155], v[16:31]
	v_mfma_f32_32x32x16_bf16 v[0:15], v[164:167], v[156:159], v[0:15]
	v_mfma_f32_32x32x16_bf16 v[16:31], v[48:51], v[32:35], v[16:31]
	v_mfma_f32_32x32x16_bf16 v[0:15], v[48:51], v[36:39], v[0:15]
	ds_read_b128 v[32:35], v84 offset:23040
	ds_read_b128 v[36:39], v84 offset:18432
	ds_read_b128 v[56:59], v83 offset:46080
	ds_read_b128 v[48:51], v84 offset:18464
	ds_read_b128 v[52:55], v84 offset:23072
	ds_read_b128 v[64:67], v83 offset:46112
	s_waitcnt lgkmcnt(3)
	v_mfma_f32_32x32x16_bf16 v[16:31], v[56:59], v[36:39], v[16:31]
	v_mfma_f32_32x32x16_bf16 v[0:15], v[56:59], v[32:35], v[0:15]
	global_load_dwordx4 v[32:35], v135, s[4:5] offset:640
	global_load_dwordx4 v[36:39], v136, s[4:5] offset:640
	global_load_dwordx4 v[56:59], v137, s[4:5] offset:640
	global_load_dwordx4 v[140:143], v138, s[4:5] offset:640
	global_load_dwordx4 v[144:147], v135, s[6:7] offset:640
	global_load_dwordx4 v[148:151], v136, s[6:7] offset:640
	ds_read_b128 v[152:155], v84 offset:18496
	ds_read_b128 v[156:159], v84 offset:23104
	ds_read_b128 v[164:167], v83 offset:46144
	s_waitcnt vmcnt(11)
	ds_write_b128 v82, v[40:43]
	s_waitcnt vmcnt(10)
	ds_write_b128 v82, v[44:47] offset:4608
	s_waitcnt vmcnt(9)
	ds_write_b128 v82, v[60:63] offset:9216
	s_waitcnt vmcnt(8)
	ds_write_b128 v82, v[68:71] offset:13824
	s_waitcnt lgkmcnt(7)
	v_mfma_f32_32x32x16_bf16 v[16:31], v[64:67], v[48:51], v[16:31]
	v_mfma_f32_32x32x16_bf16 v[0:15], v[64:67], v[52:55], v[0:15]
	ds_read_b128 v[40:43], v84 offset:18528
	ds_read_b128 v[44:47], v84 offset:23136
	ds_read_b128 v[48:51], v83 offset:46176
	s_waitcnt vmcnt(7)
	ds_write_b128 v82, v[72:75] offset:36864
	s_waitcnt vmcnt(6)
	ds_write_b128 v82, v[76:79] offset:41472
	s_waitcnt lgkmcnt(0)
	s_barrier
	v_mfma_f32_32x32x16_bf16 v[16:31], v[164:167], v[152:155], v[16:31]
	v_mfma_f32_32x32x16_bf16 v[0:15], v[164:167], v[156:159], v[0:15]
	v_mfma_f32_32x32x16_bf16 v[16:31], v[48:51], v[40:43], v[16:31]
	v_mfma_f32_32x32x16_bf16 v[0:15], v[48:51], v[44:47], v[0:15]
	ds_read_b128 v[40:43], v84 offset:4608
	ds_read_b128 v[44:47], v84
	ds_read_b128 v[60:63], v83 offset:36864
	ds_read_b128 v[48:51], v84 offset:32
	ds_read_b128 v[52:55], v84 offset:4640
	ds_read_b128 v[64:67], v83 offset:36896
	s_waitcnt lgkmcnt(3)
	v_mfma_f32_32x32x16_bf16 v[16:31], v[60:63], v[44:47], v[16:31]
	v_mfma_f32_32x32x16_bf16 v[0:15], v[60:63], v[40:43], v[0:15]
	global_load_dwordx4 v[40:43], v135, s[4:5] offset:768
	global_load_dwordx4 v[44:47], v136, s[4:5] offset:768
	global_load_dwordx4 v[60:63], v137, s[4:5] offset:768
	global_load_dwordx4 v[68:71], v138, s[4:5] offset:768
	global_load_dwordx4 v[72:75], v135, s[6:7] offset:768
	global_load_dwordx4 v[76:79], v136, s[6:7] offset:768
	ds_read_b128 v[152:155], v84 offset:64
	ds_read_b128 v[156:159], v84 offset:4672
	ds_read_b128 v[164:167], v83 offset:36928
	s_waitcnt vmcnt(11)
	ds_write_b128 v82, v[32:35] offset:18432
	s_waitcnt vmcnt(10)
	ds_write_b128 v82, v[36:39] offset:23040
	s_waitcnt vmcnt(9)
	ds_write_b128 v82, v[56:59] offset:27648
	s_waitcnt vmcnt(8)
	ds_write_b128 v82, v[140:143] offset:32256
	s_waitcnt lgkmcnt(7)
	v_mfma_f32_32x32x16_bf16 v[16:31], v[64:67], v[48:51], v[16:31]
	v_mfma_f32_32x32x16_bf16 v[0:15], v[64:67], v[52:55], v[0:15]
	ds_read_b128 v[32:35], v84 offset:96
	ds_read_b128 v[36:39], v84 offset:4704
	ds_read_b128 v[48:51], v83 offset:36960
	s_waitcnt vmcnt(7)
	ds_write_b128 v82, v[144:147] offset:46080
	s_waitcnt vmcnt(6)
	ds_write_b128 v82, v[148:151] offset:50688
	s_waitcnt lgkmcnt(0)
	s_barrier
	v_mfma_f32_32x32x16_bf16 v[16:31], v[164:167], v[152:155], v[16:31]
	v_mfma_f32_32x32x16_bf16 v[0:15], v[164:167], v[156:159], v[0:15]
	v_mfma_f32_32x32x16_bf16 v[16:31], v[48:51], v[32:35], v[16:31]
	v_mfma_f32_32x32x16_bf16 v[0:15], v[48:51], v[36:39], v[0:15]
	ds_read_b128 v[32:35], v84 offset:23040
	ds_read_b128 v[36:39], v84 offset:18432
	ds_read_b128 v[56:59], v83 offset:46080
	ds_read_b128 v[48:51], v84 offset:18464
	ds_read_b128 v[52:55], v84 offset:23072
	ds_read_b128 v[64:67], v83 offset:46112
	s_waitcnt lgkmcnt(3)
	v_mfma_f32_32x32x16_bf16 v[16:31], v[56:59], v[36:39], v[16:31]
	v_mfma_f32_32x32x16_bf16 v[0:15], v[56:59], v[32:35], v[0:15]
	global_load_dwordx4 v[32:35], v135, s[4:5] offset:896
	global_load_dwordx4 v[36:39], v136, s[4:5] offset:896
	global_load_dwordx4 v[56:59], v137, s[4:5] offset:896
	global_load_dwordx4 v[140:143], v138, s[4:5] offset:896
	global_load_dwordx4 v[144:147], v135, s[6:7] offset:896
	global_load_dwordx4 v[148:151], v136, s[6:7] offset:896
	ds_read_b128 v[152:155], v84 offset:18496
	ds_read_b128 v[156:159], v84 offset:23104
	ds_read_b128 v[164:167], v83 offset:46144
	s_waitcnt vmcnt(11)
	ds_write_b128 v82, v[40:43]
	s_waitcnt vmcnt(10)
	ds_write_b128 v82, v[44:47] offset:4608
	s_waitcnt vmcnt(9)
	ds_write_b128 v82, v[60:63] offset:9216
	s_waitcnt vmcnt(8)
	ds_write_b128 v82, v[68:71] offset:13824
	s_waitcnt lgkmcnt(7)
	v_mfma_f32_32x32x16_bf16 v[16:31], v[64:67], v[48:51], v[16:31]
	v_mfma_f32_32x32x16_bf16 v[0:15], v[64:67], v[52:55], v[0:15]
	ds_read_b128 v[40:43], v84 offset:18528
	ds_read_b128 v[44:47], v84 offset:23136
	ds_read_b128 v[48:51], v83 offset:46176
	s_waitcnt vmcnt(7)
	ds_write_b128 v82, v[72:75] offset:36864
	s_waitcnt vmcnt(6)
	ds_write_b128 v82, v[76:79] offset:41472
	s_waitcnt lgkmcnt(0)
	s_barrier
	v_mfma_f32_32x32x16_bf16 v[16:31], v[164:167], v[152:155], v[16:31]
	v_mfma_f32_32x32x16_bf16 v[0:15], v[164:167], v[156:159], v[0:15]
	v_mfma_f32_32x32x16_bf16 v[16:31], v[48:51], v[40:43], v[16:31]
	v_mfma_f32_32x32x16_bf16 v[0:15], v[48:51], v[44:47], v[0:15]
	ds_read_b128 v[40:43], v84 offset:4608
	ds_read_b128 v[44:47], v84
	ds_read_b128 v[60:63], v83 offset:36864
	ds_read_b128 v[48:51], v84 offset:32
	ds_read_b128 v[52:55], v84 offset:4640
	ds_read_b128 v[64:67], v83 offset:36896
	s_waitcnt lgkmcnt(3)
	v_mfma_f32_32x32x16_bf16 v[16:31], v[60:63], v[44:47], v[16:31]
	v_mfma_f32_32x32x16_bf16 v[0:15], v[60:63], v[40:43], v[0:15]
	global_load_dwordx4 v[40:43], v135, s[4:5] offset:1024
	global_load_dwordx4 v[44:47], v136, s[4:5] offset:1024
	global_load_dwordx4 v[60:63], v137, s[4:5] offset:1024
	global_load_dwordx4 v[68:71], v138, s[4:5] offset:1024
	global_load_dwordx4 v[72:75], v135, s[6:7] offset:1024
	global_load_dwordx4 v[76:79], v136, s[6:7] offset:1024
	ds_read_b128 v[152:155], v84 offset:64
	ds_read_b128 v[156:159], v84 offset:4672
	ds_read_b128 v[164:167], v83 offset:36928
	s_waitcnt vmcnt(11)
	ds_write_b128 v82, v[32:35] offset:18432
	s_waitcnt vmcnt(10)
	ds_write_b128 v82, v[36:39] offset:23040
	s_waitcnt vmcnt(9)
	ds_write_b128 v82, v[56:59] offset:27648
	s_waitcnt vmcnt(8)
	ds_write_b128 v82, v[140:143] offset:32256
	s_waitcnt lgkmcnt(7)
	v_mfma_f32_32x32x16_bf16 v[16:31], v[64:67], v[48:51], v[16:31]
	v_mfma_f32_32x32x16_bf16 v[0:15], v[64:67], v[52:55], v[0:15]
	ds_read_b128 v[32:35], v84 offset:96
	ds_read_b128 v[36:39], v84 offset:4704
	ds_read_b128 v[48:51], v83 offset:36960
	s_waitcnt vmcnt(7)
	ds_write_b128 v82, v[144:147] offset:46080
	s_waitcnt vmcnt(6)
	ds_write_b128 v82, v[148:151] offset:50688
	s_waitcnt lgkmcnt(0)
	s_barrier
	v_mfma_f32_32x32x16_bf16 v[16:31], v[164:167], v[152:155], v[16:31]
	v_mfma_f32_32x32x16_bf16 v[0:15], v[164:167], v[156:159], v[0:15]
	v_mfma_f32_32x32x16_bf16 v[16:31], v[48:51], v[32:35], v[16:31]
	v_mfma_f32_32x32x16_bf16 v[0:15], v[48:51], v[36:39], v[0:15]
	ds_read_b128 v[32:35], v84 offset:23040
	ds_read_b128 v[36:39], v84 offset:18432
	ds_read_b128 v[56:59], v83 offset:46080
	ds_read_b128 v[48:51], v84 offset:18464
	ds_read_b128 v[52:55], v84 offset:23072
	ds_read_b128 v[64:67], v83 offset:46112
	s_waitcnt lgkmcnt(3)
	v_mfma_f32_32x32x16_bf16 v[16:31], v[56:59], v[36:39], v[16:31]
	v_mfma_f32_32x32x16_bf16 v[0:15], v[56:59], v[32:35], v[0:15]
	global_load_dwordx4 v[32:35], v135, s[4:5] offset:1152
	global_load_dwordx4 v[36:39], v136, s[4:5] offset:1152
	global_load_dwordx4 v[56:59], v137, s[4:5] offset:1152
	global_load_dwordx4 v[140:143], v138, s[4:5] offset:1152
	global_load_dwordx4 v[144:147], v135, s[6:7] offset:1152
	global_load_dwordx4 v[148:151], v136, s[6:7] offset:1152
	ds_read_b128 v[152:155], v84 offset:18496
	ds_read_b128 v[156:159], v84 offset:23104
	ds_read_b128 v[164:167], v83 offset:46144
	s_waitcnt vmcnt(11)
	ds_write_b128 v82, v[40:43]
	s_waitcnt vmcnt(10)
	ds_write_b128 v82, v[44:47] offset:4608
	s_waitcnt vmcnt(9)
	ds_write_b128 v82, v[60:63] offset:9216
	s_waitcnt vmcnt(8)
	ds_write_b128 v82, v[68:71] offset:13824
	s_waitcnt lgkmcnt(7)
	v_mfma_f32_32x32x16_bf16 v[16:31], v[64:67], v[48:51], v[16:31]
	v_mfma_f32_32x32x16_bf16 v[0:15], v[64:67], v[52:55], v[0:15]
	ds_read_b128 v[40:43], v84 offset:18528
	ds_read_b128 v[44:47], v84 offset:23136
	ds_read_b128 v[48:51], v83 offset:46176
	s_waitcnt vmcnt(7)
	ds_write_b128 v82, v[72:75] offset:36864
	s_waitcnt vmcnt(6)
	ds_write_b128 v82, v[76:79] offset:41472
	s_waitcnt lgkmcnt(0)
	s_barrier
	v_mfma_f32_32x32x16_bf16 v[16:31], v[164:167], v[152:155], v[16:31]
	v_mfma_f32_32x32x16_bf16 v[0:15], v[164:167], v[156:159], v[0:15]
	v_mfma_f32_32x32x16_bf16 v[16:31], v[48:51], v[40:43], v[16:31]
	v_mfma_f32_32x32x16_bf16 v[0:15], v[48:51], v[44:47], v[0:15]
	ds_read_b128 v[40:43], v84 offset:4608
	ds_read_b128 v[44:47], v84
	ds_read_b128 v[60:63], v83 offset:36864
	ds_read_b128 v[48:51], v84 offset:32
	ds_read_b128 v[52:55], v84 offset:4640
	ds_read_b128 v[64:67], v83 offset:36896
	s_waitcnt lgkmcnt(3)
	v_mfma_f32_32x32x16_bf16 v[16:31], v[60:63], v[44:47], v[16:31]
	v_mfma_f32_32x32x16_bf16 v[0:15], v[60:63], v[40:43], v[0:15]
	global_load_dwordx4 v[40:43], v135, s[4:5] offset:1280
	global_load_dwordx4 v[44:47], v136, s[4:5] offset:1280
	global_load_dwordx4 v[60:63], v137, s[4:5] offset:1280
	global_load_dwordx4 v[68:71], v138, s[4:5] offset:1280
	global_load_dwordx4 v[72:75], v135, s[6:7] offset:1280
	global_load_dwordx4 v[76:79], v136, s[6:7] offset:1280
	ds_read_b128 v[152:155], v84 offset:64
	ds_read_b128 v[156:159], v84 offset:4672
	ds_read_b128 v[164:167], v83 offset:36928
	s_waitcnt vmcnt(11)
	ds_write_b128 v82, v[32:35] offset:18432
	s_waitcnt vmcnt(10)
	ds_write_b128 v82, v[36:39] offset:23040
	s_waitcnt vmcnt(9)
	ds_write_b128 v82, v[56:59] offset:27648
	s_waitcnt vmcnt(8)
	ds_write_b128 v82, v[140:143] offset:32256
	s_waitcnt lgkmcnt(7)
	v_mfma_f32_32x32x16_bf16 v[16:31], v[64:67], v[48:51], v[16:31]
	v_mfma_f32_32x32x16_bf16 v[0:15], v[64:67], v[52:55], v[0:15]
	ds_read_b128 v[32:35], v84 offset:96
	ds_read_b128 v[36:39], v84 offset:4704
	ds_read_b128 v[48:51], v83 offset:36960
	s_waitcnt vmcnt(7)
	ds_write_b128 v82, v[144:147] offset:46080
	s_waitcnt vmcnt(6)
	ds_write_b128 v82, v[148:151] offset:50688
	s_waitcnt lgkmcnt(0)
	s_barrier
	v_mfma_f32_32x32x16_bf16 v[16:31], v[164:167], v[152:155], v[16:31]
	v_mfma_f32_32x32x16_bf16 v[0:15], v[164:167], v[156:159], v[0:15]
	v_mfma_f32_32x32x16_bf16 v[16:31], v[48:51], v[32:35], v[16:31]
	v_mfma_f32_32x32x16_bf16 v[0:15], v[48:51], v[36:39], v[0:15]
	ds_read_b128 v[32:35], v84 offset:23040
	ds_read_b128 v[36:39], v84 offset:18432
	ds_read_b128 v[56:59], v83 offset:46080
	ds_read_b128 v[48:51], v84 offset:18464
	ds_read_b128 v[52:55], v84 offset:23072
	ds_read_b128 v[64:67], v83 offset:46112
	s_waitcnt lgkmcnt(3)
	v_mfma_f32_32x32x16_bf16 v[16:31], v[56:59], v[36:39], v[16:31]
	v_mfma_f32_32x32x16_bf16 v[0:15], v[56:59], v[32:35], v[0:15]
	global_load_dwordx4 v[32:35], v135, s[4:5] offset:1408
	global_load_dwordx4 v[36:39], v136, s[4:5] offset:1408
	global_load_dwordx4 v[56:59], v137, s[4:5] offset:1408
	global_load_dwordx4 v[140:143], v138, s[4:5] offset:1408
	global_load_dwordx4 v[144:147], v135, s[6:7] offset:1408
	global_load_dwordx4 v[148:151], v136, s[6:7] offset:1408
	ds_read_b128 v[152:155], v84 offset:18496
	ds_read_b128 v[156:159], v84 offset:23104
	ds_read_b128 v[164:167], v83 offset:46144
	s_waitcnt vmcnt(11)
	ds_write_b128 v82, v[40:43]
	s_waitcnt vmcnt(10)
	ds_write_b128 v82, v[44:47] offset:4608
	s_waitcnt vmcnt(9)
	ds_write_b128 v82, v[60:63] offset:9216
	s_waitcnt vmcnt(8)
	ds_write_b128 v82, v[68:71] offset:13824
	s_waitcnt lgkmcnt(7)
	v_mfma_f32_32x32x16_bf16 v[16:31], v[64:67], v[48:51], v[16:31]
	v_mfma_f32_32x32x16_bf16 v[0:15], v[64:67], v[52:55], v[0:15]
	ds_read_b128 v[40:43], v84 offset:18528
	ds_read_b128 v[44:47], v84 offset:23136
	ds_read_b128 v[48:51], v83 offset:46176
	s_waitcnt vmcnt(7)
	ds_write_b128 v82, v[72:75] offset:36864
	s_waitcnt vmcnt(6)
	ds_write_b128 v82, v[76:79] offset:41472
	s_waitcnt lgkmcnt(0)
	s_barrier
	v_mfma_f32_32x32x16_bf16 v[16:31], v[164:167], v[152:155], v[16:31]
	v_mfma_f32_32x32x16_bf16 v[0:15], v[164:167], v[156:159], v[0:15]
	v_mfma_f32_32x32x16_bf16 v[16:31], v[48:51], v[40:43], v[16:31]
	v_mfma_f32_32x32x16_bf16 v[0:15], v[48:51], v[44:47], v[0:15]
	ds_read_b128 v[40:43], v84 offset:4608
	ds_read_b128 v[44:47], v84
	ds_read_b128 v[60:63], v83 offset:36864
	ds_read_b128 v[48:51], v84 offset:32
	ds_read_b128 v[52:55], v84 offset:4640
	ds_read_b128 v[64:67], v83 offset:36896
	s_waitcnt lgkmcnt(3)
	v_mfma_f32_32x32x16_bf16 v[16:31], v[60:63], v[44:47], v[16:31]
	v_mfma_f32_32x32x16_bf16 v[0:15], v[60:63], v[40:43], v[0:15]
	global_load_dwordx4 v[40:43], v135, s[4:5] offset:1536
	global_load_dwordx4 v[44:47], v136, s[4:5] offset:1536
	global_load_dwordx4 v[60:63], v137, s[4:5] offset:1536
	global_load_dwordx4 v[68:71], v138, s[4:5] offset:1536
	global_load_dwordx4 v[72:75], v135, s[6:7] offset:1536
	global_load_dwordx4 v[76:79], v136, s[6:7] offset:1536
	ds_read_b128 v[152:155], v84 offset:64
	ds_read_b128 v[156:159], v84 offset:4672
	ds_read_b128 v[164:167], v83 offset:36928
	s_waitcnt vmcnt(11)
	ds_write_b128 v82, v[32:35] offset:18432
	s_waitcnt vmcnt(10)
	ds_write_b128 v82, v[36:39] offset:23040
	s_waitcnt vmcnt(9)
	ds_write_b128 v82, v[56:59] offset:27648
	s_waitcnt vmcnt(8)
	ds_write_b128 v82, v[140:143] offset:32256
	s_waitcnt lgkmcnt(7)
	v_mfma_f32_32x32x16_bf16 v[16:31], v[64:67], v[48:51], v[16:31]
	v_mfma_f32_32x32x16_bf16 v[0:15], v[64:67], v[52:55], v[0:15]
	ds_read_b128 v[32:35], v84 offset:96
	ds_read_b128 v[36:39], v84 offset:4704
	ds_read_b128 v[48:51], v83 offset:36960
	s_waitcnt vmcnt(7)
	ds_write_b128 v82, v[144:147] offset:46080
	s_waitcnt vmcnt(6)
	ds_write_b128 v82, v[148:151] offset:50688
	s_waitcnt lgkmcnt(0)
	s_barrier
	v_mfma_f32_32x32x16_bf16 v[16:31], v[164:167], v[152:155], v[16:31]
	v_mfma_f32_32x32x16_bf16 v[0:15], v[164:167], v[156:159], v[0:15]
	v_mfma_f32_32x32x16_bf16 v[16:31], v[48:51], v[32:35], v[16:31]
	v_mfma_f32_32x32x16_bf16 v[0:15], v[48:51], v[36:39], v[0:15]
	ds_read_b128 v[32:35], v84 offset:23040
	ds_read_b128 v[36:39], v84 offset:18432
	ds_read_b128 v[56:59], v83 offset:46080
	ds_read_b128 v[48:51], v84 offset:18464
	ds_read_b128 v[52:55], v84 offset:23072
	ds_read_b128 v[64:67], v83 offset:46112
	s_waitcnt lgkmcnt(3)
	v_mfma_f32_32x32x16_bf16 v[16:31], v[56:59], v[36:39], v[16:31]
	v_mfma_f32_32x32x16_bf16 v[0:15], v[56:59], v[32:35], v[0:15]
	global_load_dwordx4 v[32:35], v135, s[4:5] offset:1664
	global_load_dwordx4 v[36:39], v136, s[4:5] offset:1664
	global_load_dwordx4 v[56:59], v137, s[4:5] offset:1664
	global_load_dwordx4 v[140:143], v138, s[4:5] offset:1664
	global_load_dwordx4 v[144:147], v135, s[6:7] offset:1664
	global_load_dwordx4 v[148:151], v136, s[6:7] offset:1664
	ds_read_b128 v[152:155], v84 offset:18496
	ds_read_b128 v[156:159], v84 offset:23104
	ds_read_b128 v[164:167], v83 offset:46144
	s_waitcnt vmcnt(11)
	ds_write_b128 v82, v[40:43]
	s_waitcnt vmcnt(10)
	ds_write_b128 v82, v[44:47] offset:4608
	s_waitcnt vmcnt(9)
	ds_write_b128 v82, v[60:63] offset:9216
	s_waitcnt vmcnt(8)
	ds_write_b128 v82, v[68:71] offset:13824
	s_waitcnt lgkmcnt(7)
	v_mfma_f32_32x32x16_bf16 v[16:31], v[64:67], v[48:51], v[16:31]
	v_mfma_f32_32x32x16_bf16 v[0:15], v[64:67], v[52:55], v[0:15]
	ds_read_b128 v[40:43], v84 offset:18528
	ds_read_b128 v[44:47], v84 offset:23136
	ds_read_b128 v[48:51], v83 offset:46176
	s_waitcnt vmcnt(7)
	ds_write_b128 v82, v[72:75] offset:36864
	s_waitcnt vmcnt(6)
	ds_write_b128 v82, v[76:79] offset:41472
	s_waitcnt lgkmcnt(0)
	s_barrier
	v_mfma_f32_32x32x16_bf16 v[16:31], v[164:167], v[152:155], v[16:31]
	ds_read_b128 v[60:63], v83 offset:36864
	ds_read_b128 v[52:55], v84 offset:4640
	global_load_dwordx4 v[68:71], v138, s[4:5] offset:1792
	ds_read_b128 v[64:67], v83 offset:36896
	ds_read_b128 v[152:155], v84 offset:64
	global_load_dwordx4 v[72:75], v135, s[6:7] offset:1792
	v_mfma_f32_32x32x16_bf16 v[0:15], v[164:167], v[156:159], v[0:15]
	ds_read_b128 v[156:159], v84 offset:4672
	global_load_dwordx4 v[76:79], v136, s[6:7] offset:1792
	ds_read_b128 v[164:167], v83 offset:36928
	v_mfma_f32_32x32x16_bf16 v[16:31], v[48:51], v[40:43], v[16:31]
	ds_read_b128 v[40:43], v84 offset:4608
	v_mfma_f32_32x32x16_bf16 v[0:15], v[48:51], v[44:47], v[0:15]
	ds_read_b128 v[44:47], v84
	ds_read_b128 v[48:51], v84 offset:32
	s_waitcnt vmcnt(8)
	ds_write_b128 v82, v[32:35] offset:18432
	s_waitcnt lgkmcnt(2)
	v_mfma_f32_32x32x16_bf16 v[16:31], v[60:63], v[44:47], v[16:31]
	global_load_dwordx4 v[44:47], v136, s[4:5] offset:1792
	s_waitcnt vmcnt(8)
	ds_write_b128 v82, v[36:39] offset:23040
	s_waitcnt vmcnt(7)
	ds_write_b128 v82, v[56:59] offset:27648
	s_waitcnt vmcnt(6)
	ds_write_b128 v82, v[140:143] offset:32256
	ds_read_b128 v[32:35], v84 offset:96
	ds_read_b128 v[36:39], v84 offset:4704
	v_mfma_f32_32x32x16_bf16 v[0:15], v[60:63], v[40:43], v[0:15]
	global_load_dwordx4 v[40:43], v135, s[4:5] offset:1792
	global_load_dwordx4 v[60:63], v137, s[4:5] offset:1792
	s_waitcnt lgkmcnt(6)
	v_mfma_f32_32x32x16_bf16 v[16:31], v[64:67], v[48:51], v[16:31]
	ds_read_b128 v[48:51], v83 offset:36960
	s_waitcnt vmcnt(7)
	ds_write_b128 v82, v[144:147] offset:46080
	s_waitcnt vmcnt(6)
	ds_write_b128 v82, v[148:151] offset:50688
	s_waitcnt lgkmcnt(0)
	s_barrier
	ds_read_b128 v[56:59], v83 offset:46080
	v_mfma_f32_32x32x16_bf16 v[0:15], v[64:67], v[52:55], v[0:15]
	global_load_dwordx4 v[138:141], v138, s[4:5] offset:1920
	ds_read_b128 v[52:55], v84 offset:23072
	global_load_dwordx4 v[142:145], v135, s[6:7] offset:1920
	global_load_dwordx4 v[146:149], v136, s[6:7] offset:1920
	ds_read_b128 v[64:67], v83 offset:46112
	v_mfma_f32_32x32x16_bf16 v[16:31], v[164:167], v[152:155], v[16:31]
	ds_read_b128 v[150:153], v84 offset:18496
	v_mfma_f32_32x32x16_bf16 v[0:15], v[164:167], v[156:159], v[0:15]
	ds_read_b128 v[154:157], v84 offset:23104
	ds_read_b128 v[164:167], v83 offset:46144
	v_mfma_f32_32x32x16_bf16 v[16:31], v[48:51], v[32:35], v[16:31]
	ds_read_b128 v[32:35], v84 offset:23040
	v_mfma_f32_32x32x16_bf16 v[0:15], v[48:51], v[36:39], v[0:15]
	ds_read_b128 v[36:39], v84 offset:18432
	ds_read_b128 v[48:51], v84 offset:18464
	s_waitcnt vmcnt(8)
	ds_write_b128 v82, v[68:71] offset:13824
	s_waitcnt vmcnt(5)
	ds_write_b128 v82, v[44:47] offset:4608
	s_waitcnt lgkmcnt(3)
	v_mfma_f32_32x32x16_bf16 v[16:31], v[56:59], v[36:39], v[16:31]
	global_load_dwordx4 v[36:39], v136, s[4:5] offset:1920
	s_waitcnt vmcnt(5)
	ds_write_b128 v82, v[40:43]
	v_mfma_f32_32x32x16_bf16 v[0:15], v[56:59], v[32:35], v[0:15]
	global_load_dwordx4 v[32:35], v135, s[4:5] offset:1920
	global_load_dwordx4 v[56:59], v137, s[4:5] offset:1920
	s_waitcnt vmcnt(6)
	ds_write_b128 v82, v[60:63] offset:9216
	ds_read_b128 v[40:43], v84 offset:18528
	ds_read_b128 v[44:47], v84 offset:23136
	s_waitcnt lgkmcnt(6)
	v_mfma_f32_32x32x16_bf16 v[16:31], v[64:67], v[48:51], v[16:31]
	ds_read_b128 v[48:51], v83 offset:46176
	ds_write_b128 v82, v[72:75] offset:36864
	ds_write_b128 v82, v[76:79] offset:41472
	s_waitcnt lgkmcnt(0)
	s_barrier
	ds_read_b128 v[60:63], v84 offset:32
	v_mfma_f32_32x32x16_bf16 v[0:15], v[64:67], v[52:55], v[0:15]
	ds_read_b128 v[52:55], v84
	ds_read_b128 v[64:67], v83 offset:36928
	v_mfma_f32_32x32x16_bf16 v[16:31], v[164:167], v[150:153], v[16:31]
	v_mfma_f32_32x32x16_bf16 v[0:15], v[164:167], v[154:157], v[0:15]
	v_mfma_f32_32x32x16_bf16 v[16:31], v[48:51], v[40:43], v[16:31]
	ds_read_b128 v[40:43], v84 offset:4608
	v_mfma_f32_32x32x16_bf16 v[0:15], v[48:51], v[44:47], v[0:15]
	ds_read_b128 v[44:47], v83 offset:36864
	ds_read_b128 v[48:51], v83 offset:36896
	s_waitcnt lgkmcnt(1)
	v_mfma_f32_32x32x16_bf16 v[0:15], v[44:47], v[40:43], v[0:15]
	ds_read_b128 v[40:43], v84 offset:4640
	v_mfma_f32_32x32x16_bf16 v[16:31], v[44:47], v[52:55], v[16:31]
	ds_read_b128 v[52:55], v84 offset:4672
	ds_read_b128 v[44:47], v84 offset:64
	s_waitcnt vmcnt(5)
	ds_write_b128 v82, v[138:141] offset:32256
	s_waitcnt vmcnt(2)
	ds_write_b128 v82, v[36:39] offset:23040
	s_waitcnt lgkmcnt(4)
	v_mfma_f32_32x32x16_bf16 v[0:15], v[48:51], v[40:43], v[0:15]
	s_waitcnt vmcnt(1)
	ds_write_b128 v82, v[32:35] offset:18432
	v_mfma_f32_32x32x16_bf16 v[16:31], v[48:51], v[60:63], v[16:31]
	s_waitcnt vmcnt(0)
	ds_write_b128 v82, v[56:59] offset:27648
	ds_read_b128 v[36:39], v84 offset:4704
	ds_read_b128 v[32:35], v84 offset:96
	ds_read_b128 v[40:43], v83 offset:36960
	ds_write_b128 v82, v[142:145] offset:46080
	ds_write_b128 v82, v[146:149] offset:50688
	s_waitcnt lgkmcnt(0)
	v_mfma_f32_32x32x16_bf16 v[0:15], v[64:67], v[52:55], v[0:15]
	s_barrier
	ds_read_b128 v[48:51], v83 offset:46080
	ds_read_b128 v[52:55], v83 offset:46112
	ds_read_b128 v[56:59], v84 offset:18528
	ds_read_b128 v[60:63], v84 offset:23136
	v_mfma_f32_32x32x16_bf16 v[16:31], v[64:67], v[44:47], v[16:31]
	ds_read_b128 v[64:67], v83 offset:46176
	ds_read_b128 v[44:47], v84 offset:23072
	v_mfma_f32_32x32x16_bf16 v[0:15], v[40:43], v[36:39], v[0:15]
	ds_read_b128 v[36:39], v84 offset:18432
	v_mfma_f32_32x32x16_bf16 v[16:31], v[40:43], v[32:35], v[16:31]
	ds_read_b128 v[32:35], v84 offset:23040
	ds_read_b128 v[40:43], v84 offset:18464
	s_waitcnt lgkmcnt(2)
	v_mfma_f32_32x32x16_bf16 v[16:31], v[48:51], v[36:39], v[16:31]
	ds_read_b128 v[36:39], v84 offset:23104
	s_waitcnt lgkmcnt(2)
	v_mfma_f32_32x32x16_bf16 v[0:15], v[48:51], v[32:35], v[0:15]
	ds_read_b128 v[32:35], v84 offset:18496
	ds_read_b128 v[48:51], v83 offset:46144
	s_waitcnt lgkmcnt(0)
	s_barrier
	v_mfma_f32_32x32x16_bf16 v[16:31], v[52:55], v[40:43], v[16:31]
	v_mfma_f32_32x32x16_bf16 v[16:31], v[48:51], v[32:35], v[16:31]
	v_mfma_f32_32x32x16_bf16 v[16:31], v[64:67], v[56:59], v[16:31]
	v_mfma_f32_32x32x16_bf16 v[0:15], v[52:55], v[44:47], v[0:15]
	v_mfma_f32_32x32x16_bf16 v[0:15], v[48:51], v[36:39], v[0:15]
	v_mfma_f32_32x32x16_bf16 v[0:15], v[64:67], v[60:63], v[0:15]
	s_waitcnt vmcnt(0)
	v_add_f32_e32 v210, v210, v211
	v_add_f32_e32 v212, v212, v213
	v_add_f32_e32 v214, v214, v215
	v_add_f32_e32 v216, v216, v217
	v_add_f32_e32 v210, v210, v212
	v_add_f32_e32 v214, v214, v216
	v_add_f32_e32 v210, v210, v214
	v_fmamk_f32 v250, v210, 0x3a800000, v187
	v_add_f32_e32 v226, v226, v227
	v_add_f32_e32 v228, v228, v229
	v_add_f32_e32 v230, v230, v231
	v_add_f32_e32 v232, v232, v233
	v_add_f32_e32 v226, v226, v228
	v_add_f32_e32 v230, v230, v232
	v_add_f32_e32 v226, v226, v230
	v_fmamk_f32 v249, v226, 0x3a800000, v187
	v_rsq_f32_e32 v250, v250
	v_rsq_f32_e32 v249, v249
	s_nop 0
	s_barrier
	v_readfirstlane_b32 s18, v186
	v_and_b32_e32 v64, 31, v186
	v_bfe_u32 v67, v186, 5, 1
	s_lshr_b32 s18, s18, 6
	s_and_b32 s19, s18, 1
	s_lshr_b32 s26, s18, 1
	s_lshl_b32 s26, s26, 6
	v_add_u32_e32 v64, s26, v64
	v_mul_u32_u24_e32 v64, 0x110, v64
	v_lshl_add_u32 v64, v67, 4, v64
	s_lshl_b32 s26, s19, 7
	v_add_u32_e32 v64, s26, v64
	v_and_b32_e32 v66, 63, v186
	v_lshrrev_b32_e32 v65, 4, v66
	v_and_b32_e32 v66, 15, v66
	s_lshl_b32 s26, s18, 5
	v_add_u32_e32 v65, s26, v65
	v_lshlrev_b32_e32 v67, 12, v65
	v_lshl_add_u32 v67, v66, 4, v67
	v_mul_u32_u24_e32 v65, 0x110, v65
	v_lshl_add_u32 v65, v66, 4, v65
	s_lshl_b32 s18, s0, 12
	s_lshl_b32 s19, s2, 2
	s_add_u32 s18, s18, s19
	s_add_u32 s20, s86, s18
	s_addc_u32 s21, s87, 0
	s_mov_b32 s26, s20
	s_mov_b32 s27, s21
	global_load_dwordx4 v[68:71], v67, s[20:21]
	s_add_u32 s20, s20, 0x4000
	s_addc_u32 s21, s21, 0
	global_load_dwordx4 v[72:75], v67, s[20:21]
	s_add_u32 s20, s20, 0x4000
	s_addc_u32 s21, s21, 0
	global_load_dwordx4 v[76:79], v67, s[20:21]
	s_add_u32 s20, s20, 0x4000
	s_addc_u32 s21, s21, 0
	global_load_dwordx4 v[80:83], v67, s[20:21]
	s_add_u32 s20, s20, 0x4000
	s_addc_u32 s21, s21, 0
	global_load_dwordx4 v[84:87], v67, s[20:21]
	s_add_u32 s20, s20, 0x4000
	s_addc_u32 s21, s21, 0
	global_load_dwordx4 v[88:91], v67, s[20:21]
	s_add_u32 s20, s20, 0x4000
	s_addc_u32 s21, s21, 0
	global_load_dwordx4 v[92:95], v67, s[20:21]
	s_add_u32 s20, s20, 0x4000
	s_addc_u32 s21, s21, 0
	global_load_dwordx4 v[96:99], v67, s[20:21]
	v_mul_f32_e32 v16, v250, v16
	v_mul_f32_e32 v17, v250, v17
	v_mul_f32_e32 v18, v250, v18
	v_mul_f32_e32 v19, v250, v19
	v_mul_f32_e32 v108, 0xbfb8aa3b, v16
	v_mul_f32_e32 v109, 0xbfb8aa3b, v17
	v_mul_f32_e32 v110, 0xbfb8aa3b, v18
	v_mul_f32_e32 v111, 0xbfb8aa3b, v19
	v_exp_f32_e32 v108, v108
	v_exp_f32_e32 v109, v109
	v_exp_f32_e32 v110, v110
	v_exp_f32_e32 v111, v111
	v_lshlrev_b32_e32 v112, 16, v134
	v_and_b32_e32 v113, 0xffff0000, v134
	v_lshlrev_b32_e32 v114, 16, v133
	v_and_b32_e32 v115, 0xffff0000, v133
	v_add_f32_e32 v108, 1.0, v108
	v_add_f32_e32 v109, 1.0, v109
	v_add_f32_e32 v110, 1.0, v110
	v_add_f32_e32 v111, 1.0, v111
	v_rcp_f32_e32 v108, v108
	v_rcp_f32_e32 v109, v109
	v_rcp_f32_e32 v110, v110
	v_rcp_f32_e32 v111, v111
	s_nop 0
	v_mul_f32_e32 v100, v108, v112
	v_mul_f32_e32 v101, v109, v113
	v_mul_f32_e32 v102, v110, v114
	v_mul_f32_e32 v103, v111, v115
	ds_write_b128 v64, v[100:103]
	v_mul_f32_e32 v20, v250, v20
	v_mul_f32_e32 v21, v250, v21
	v_mul_f32_e32 v22, v250, v22
	v_mul_f32_e32 v23, v250, v23
	v_mul_f32_e32 v108, 0xbfb8aa3b, v20
	v_mul_f32_e32 v109, 0xbfb8aa3b, v21
	v_mul_f32_e32 v110, 0xbfb8aa3b, v22
	v_mul_f32_e32 v111, 0xbfb8aa3b, v23
	v_exp_f32_e32 v108, v108
	v_exp_f32_e32 v109, v109
	v_exp_f32_e32 v110, v110
	v_exp_f32_e32 v111, v111
	v_lshlrev_b32_e32 v112, 16, v132
	v_and_b32_e32 v113, 0xffff0000, v132
	v_lshlrev_b32_e32 v114, 16, v131
	v_and_b32_e32 v115, 0xffff0000, v131
	v_add_f32_e32 v108, 1.0, v108
	v_add_f32_e32 v109, 1.0, v109
	v_add_f32_e32 v110, 1.0, v110
	v_add_f32_e32 v111, 1.0, v111
	v_rcp_f32_e32 v108, v108
	v_rcp_f32_e32 v109, v109
	v_rcp_f32_e32 v110, v110
	v_rcp_f32_e32 v111, v111
	s_nop 0
	v_mul_f32_e32 v104, v108, v112
	v_mul_f32_e32 v105, v109, v113
	v_mul_f32_e32 v106, v110, v114
	v_mul_f32_e32 v107, v111, v115
	ds_write_b128 v64, v[104:107] offset:32
	v_mul_f32_e32 v24, v250, v24
	v_mul_f32_e32 v25, v250, v25
	v_mul_f32_e32 v26, v250, v26
	v_mul_f32_e32 v27, v250, v27
	v_mul_f32_e32 v108, 0xbfb8aa3b, v24
	v_mul_f32_e32 v109, 0xbfb8aa3b, v25
	v_mul_f32_e32 v110, 0xbfb8aa3b, v26
	v_mul_f32_e32 v111, 0xbfb8aa3b, v27
	v_exp_f32_e32 v108, v108
	v_exp_f32_e32 v109, v109
	v_exp_f32_e32 v110, v110
	v_exp_f32_e32 v111, v111
	v_lshlrev_b32_e32 v112, 16, v130
	v_and_b32_e32 v113, 0xffff0000, v130
	v_lshlrev_b32_e32 v114, 16, v129
	v_and_b32_e32 v115, 0xffff0000, v129
	v_add_f32_e32 v108, 1.0, v108
	v_add_f32_e32 v109, 1.0, v109
	v_add_f32_e32 v110, 1.0, v110
	v_add_f32_e32 v111, 1.0, v111
	v_rcp_f32_e32 v108, v108
	v_rcp_f32_e32 v109, v109
	v_rcp_f32_e32 v110, v110
	v_rcp_f32_e32 v111, v111
	s_nop 0
	v_mul_f32_e32 v100, v108, v112
	v_mul_f32_e32 v101, v109, v113
	v_mul_f32_e32 v102, v110, v114
	v_mul_f32_e32 v103, v111, v115
	ds_write_b128 v64, v[100:103] offset:64
	v_mul_f32_e32 v28, v250, v28
	v_mul_f32_e32 v29, v250, v29
	v_mul_f32_e32 v30, v250, v30
	v_mul_f32_e32 v31, v250, v31
	v_mul_f32_e32 v108, 0xbfb8aa3b, v28
	v_mul_f32_e32 v109, 0xbfb8aa3b, v29
	v_mul_f32_e32 v110, 0xbfb8aa3b, v30
	v_mul_f32_e32 v111, 0xbfb8aa3b, v31
	v_exp_f32_e32 v108, v108
	v_exp_f32_e32 v109, v109
	v_exp_f32_e32 v110, v110
	v_exp_f32_e32 v111, v111
	v_lshlrev_b32_e32 v112, 16, v128
	v_and_b32_e32 v113, 0xffff0000, v128
	v_lshlrev_b32_e32 v114, 16, v127
	v_and_b32_e32 v115, 0xffff0000, v127
	v_add_f32_e32 v108, 1.0, v108
	v_add_f32_e32 v109, 1.0, v109
	v_add_f32_e32 v110, 1.0, v110
	v_add_f32_e32 v111, 1.0, v111
	v_rcp_f32_e32 v108, v108
	v_rcp_f32_e32 v109, v109
	v_rcp_f32_e32 v110, v110
	v_rcp_f32_e32 v111, v111
	s_nop 0
	v_mul_f32_e32 v104, v108, v112
	v_mul_f32_e32 v105, v109, v113
	v_mul_f32_e32 v106, v110, v114
	v_mul_f32_e32 v107, v111, v115
	ds_write_b128 v64, v[104:107] offset:96
	v_mul_f32_e32 v0, v249, v0
	v_mul_f32_e32 v1, v249, v1
	v_mul_f32_e32 v2, v249, v2
	v_mul_f32_e32 v3, v249, v3
	v_mul_f32_e32 v108, 0xbfb8aa3b, v0
	v_mul_f32_e32 v109, 0xbfb8aa3b, v1
	v_mul_f32_e32 v110, 0xbfb8aa3b, v2
	v_mul_f32_e32 v111, 0xbfb8aa3b, v3
	v_exp_f32_e32 v108, v108
	v_exp_f32_e32 v109, v109
	v_exp_f32_e32 v110, v110
	v_exp_f32_e32 v111, v111
	v_lshlrev_b32_e32 v112, 16, v126
	v_and_b32_e32 v113, 0xffff0000, v126
	v_lshlrev_b32_e32 v114, 16, v125
	v_and_b32_e32 v115, 0xffff0000, v125
	v_add_f32_e32 v108, 1.0, v108
	v_add_f32_e32 v109, 1.0, v109
	v_add_f32_e32 v110, 1.0, v110
	v_add_f32_e32 v111, 1.0, v111
	v_rcp_f32_e32 v108, v108
	v_rcp_f32_e32 v109, v109
	v_rcp_f32_e32 v110, v110
	v_rcp_f32_e32 v111, v111
	s_nop 0
	v_mul_f32_e32 v100, v108, v112
	v_mul_f32_e32 v101, v109, v113
	v_mul_f32_e32 v102, v110, v114
	v_mul_f32_e32 v103, v111, v115
	ds_write_b128 v64, v[100:103] offset:8704
	v_mul_f32_e32 v4, v249, v4
	v_mul_f32_e32 v5, v249, v5
	v_mul_f32_e32 v6, v249, v6
	v_mul_f32_e32 v7, v249, v7
	v_mul_f32_e32 v108, 0xbfb8aa3b, v4
	v_mul_f32_e32 v109, 0xbfb8aa3b, v5
	v_mul_f32_e32 v110, 0xbfb8aa3b, v6
	v_mul_f32_e32 v111, 0xbfb8aa3b, v7
	v_exp_f32_e32 v108, v108
	v_exp_f32_e32 v109, v109
	v_exp_f32_e32 v110, v110
	v_exp_f32_e32 v111, v111
	v_lshlrev_b32_e32 v112, 16, v124
	v_and_b32_e32 v113, 0xffff0000, v124
	v_lshlrev_b32_e32 v114, 16, v123
	v_and_b32_e32 v115, 0xffff0000, v123
	v_add_f32_e32 v108, 1.0, v108
	v_add_f32_e32 v109, 1.0, v109
	v_add_f32_e32 v110, 1.0, v110
	v_add_f32_e32 v111, 1.0, v111
	v_rcp_f32_e32 v108, v108
	v_rcp_f32_e32 v109, v109
	v_rcp_f32_e32 v110, v110
	v_rcp_f32_e32 v111, v111
	s_nop 0
	v_mul_f32_e32 v104, v108, v112
	v_mul_f32_e32 v105, v109, v113
	v_mul_f32_e32 v106, v110, v114
	v_mul_f32_e32 v107, v111, v115
	ds_write_b128 v64, v[104:107] offset:8736
	v_mul_f32_e32 v8, v249, v8
	v_mul_f32_e32 v9, v249, v9
	v_mul_f32_e32 v10, v249, v10
	v_mul_f32_e32 v11, v249, v11
	v_mul_f32_e32 v108, 0xbfb8aa3b, v8
	v_mul_f32_e32 v109, 0xbfb8aa3b, v9
	v_mul_f32_e32 v110, 0xbfb8aa3b, v10
	v_mul_f32_e32 v111, 0xbfb8aa3b, v11
	v_exp_f32_e32 v108, v108
	v_exp_f32_e32 v109, v109
	v_exp_f32_e32 v110, v110
	v_exp_f32_e32 v111, v111
	v_lshlrev_b32_e32 v112, 16, v122
	v_and_b32_e32 v113, 0xffff0000, v122
	v_lshlrev_b32_e32 v114, 16, v121
	v_and_b32_e32 v115, 0xffff0000, v121
	v_add_f32_e32 v108, 1.0, v108
	v_add_f32_e32 v109, 1.0, v109
	v_add_f32_e32 v110, 1.0, v110
	v_add_f32_e32 v111, 1.0, v111
	v_rcp_f32_e32 v108, v108
	v_rcp_f32_e32 v109, v109
	v_rcp_f32_e32 v110, v110
	v_rcp_f32_e32 v111, v111
	s_nop 0
	v_mul_f32_e32 v100, v108, v112
	v_mul_f32_e32 v101, v109, v113
	v_mul_f32_e32 v102, v110, v114
	v_mul_f32_e32 v103, v111, v115
	ds_write_b128 v64, v[100:103] offset:8768
	v_mul_f32_e32 v12, v249, v12
	v_mul_f32_e32 v13, v249, v13
	v_mul_f32_e32 v14, v249, v14
	v_mul_f32_e32 v15, v249, v15
	v_mul_f32_e32 v108, 0xbfb8aa3b, v12
	v_mul_f32_e32 v109, 0xbfb8aa3b, v13
	v_mul_f32_e32 v110, 0xbfb8aa3b, v14
	v_mul_f32_e32 v111, 0xbfb8aa3b, v15
	v_exp_f32_e32 v108, v108
	v_exp_f32_e32 v109, v109
	v_exp_f32_e32 v110, v110
	v_exp_f32_e32 v111, v111
	v_lshlrev_b32_e32 v112, 16, v120
	v_and_b32_e32 v113, 0xffff0000, v120
	v_lshlrev_b32_e32 v114, 16, v119
	v_and_b32_e32 v115, 0xffff0000, v119
	v_add_f32_e32 v108, 1.0, v108
	v_add_f32_e32 v109, 1.0, v109
	v_add_f32_e32 v110, 1.0, v110
	v_add_f32_e32 v111, 1.0, v111
	v_rcp_f32_e32 v108, v108
	v_rcp_f32_e32 v109, v109
	v_rcp_f32_e32 v110, v110
	v_rcp_f32_e32 v111, v111
	s_nop 0
	v_mul_f32_e32 v104, v108, v112
	v_mul_f32_e32 v105, v109, v113
	v_mul_f32_e32 v106, v110, v114
	v_mul_f32_e32 v107, v111, v115
	ds_write_b128 v64, v[104:107] offset:8800
	s_waitcnt lgkmcnt(0)
	s_barrier
	ds_read_b128 v[116:119], v65
	ds_read_b128 v[120:123], v65 offset:1088
	ds_read_b128 v[124:127], v65 offset:2176
	ds_read_b128 v[128:131], v65 offset:3264
	ds_read_b128 v[132:135], v65 offset:4352
	ds_read_b128 v[136:139], v65 offset:5440
	ds_read_b128 v[140:143], v65 offset:6528
	ds_read_b128 v[144:147], v65 offset:7616
	s_waitcnt lgkmcnt(7)
	s_waitcnt vmcnt(7)
	v_add_f32_e32 v68, v68, v116
	v_add_f32_e32 v69, v69, v117
	v_add_f32_e32 v70, v70, v118
	v_add_f32_e32 v71, v71, v119
	global_store_dwordx4 v67, v[68:71], s[26:27]
	s_add_u32 s26, s26, 0x4000
	s_addc_u32 s27, s27, 0
	s_waitcnt lgkmcnt(6)
	s_waitcnt vmcnt(7)
	v_add_f32_e32 v72, v72, v120
	v_add_f32_e32 v73, v73, v121
	v_add_f32_e32 v74, v74, v122
	v_add_f32_e32 v75, v75, v123
	global_store_dwordx4 v67, v[72:75], s[26:27]
	s_add_u32 s26, s26, 0x4000
	s_addc_u32 s27, s27, 0
	s_waitcnt lgkmcnt(5)
	s_waitcnt vmcnt(7)
	v_add_f32_e32 v76, v76, v124
	v_add_f32_e32 v77, v77, v125
	v_add_f32_e32 v78, v78, v126
	v_add_f32_e32 v79, v79, v127
	global_store_dwordx4 v67, v[76:79], s[26:27]
	s_add_u32 s26, s26, 0x4000
	s_addc_u32 s27, s27, 0
	s_waitcnt lgkmcnt(4)
	s_waitcnt vmcnt(7)
	v_add_f32_e32 v80, v80, v128
	v_add_f32_e32 v81, v81, v129
	v_add_f32_e32 v82, v82, v130
	v_add_f32_e32 v83, v83, v131
	global_store_dwordx4 v67, v[80:83], s[26:27]
	s_add_u32 s26, s26, 0x4000
	s_addc_u32 s27, s27, 0
	s_waitcnt lgkmcnt(3)
	s_waitcnt vmcnt(7)
	v_add_f32_e32 v84, v84, v132
	v_add_f32_e32 v85, v85, v133
	v_add_f32_e32 v86, v86, v134
	v_add_f32_e32 v87, v87, v135
	global_store_dwordx4 v67, v[84:87], s[26:27]
	s_add_u32 s26, s26, 0x4000
	s_addc_u32 s27, s27, 0
	s_waitcnt lgkmcnt(2)
	s_waitcnt vmcnt(7)
	v_add_f32_e32 v88, v88, v136
	v_add_f32_e32 v89, v89, v137
	v_add_f32_e32 v90, v90, v138
	v_add_f32_e32 v91, v91, v139
	global_store_dwordx4 v67, v[88:91], s[26:27]
	s_add_u32 s26, s26, 0x4000
	s_addc_u32 s27, s27, 0
	s_waitcnt lgkmcnt(1)
	s_waitcnt vmcnt(7)
	v_add_f32_e32 v92, v92, v140
	v_add_f32_e32 v93, v93, v141
	v_add_f32_e32 v94, v94, v142
	v_add_f32_e32 v95, v95, v143
	global_store_dwordx4 v67, v[92:95], s[26:27]
	s_add_u32 s26, s26, 0x4000
	s_addc_u32 s27, s27, 0
	s_waitcnt lgkmcnt(0)
	s_waitcnt vmcnt(7)
	v_add_f32_e32 v96, v96, v144
	v_add_f32_e32 v97, v97, v145
	v_add_f32_e32 v98, v98, v146
	v_add_f32_e32 v99, v99, v147
	global_store_dwordx4 v67, v[96:99], s[26:27]
	v_readlane_b32 s0, v252, 22
	s_nop 3
	s_add_i32 s16, s16, s0
	s_cmp_ge_i32 s16, s41
	s_cbranch_scc1 .LBB0_2461
